# filter producer: x row blocks staged once per workgroup in LDS by LDS-DMA (coalesced), fragments read from LDS; fixes the interleaving of the chain with the tap-0 branch
# speedup vs baseline: 1.0037x; 1.0037x over previous
.LBB0_224:
	s_waitcnt vmcnt(0)
	v_readlane_b32 s0, v240, 22
	v_readlane_b32 s1, v240, 23
	s_barrier
	v_and_b32_e32 v2, 63, v1
	v_and_b32_e32 v3, 31, v2
	v_lshrrev_b32_e32 v4, 5, v2
	v_lshrrev_b32_e32 v6, 6, v1
	v_mov_b32_e32 v82, 0
	s_mov_b32 s61, 0x447fc000
	v_readfirstlane_b32 s92, v6
	v_cmp_eq_u32_e64 s[14:15], 1, v4
	v_mov_b32_e32 v8, 0x3d4ccccd
	v_mov_b32_e32 v9, 0x3d4ccccd
	s_mov_b32 s93, s2
.Lpf_item:
	s_cmpk_gt_u32 s93, 0xff
	s_cbranch_scc1 .Lpf_end
	s_lshr_b32 s94, s93, 5
	s_lshl_b32 s94, s94, 3
	s_add_i32 s94, s94, s92
	s_and_b32 s95, s93, 31
	s_lshl_b32 s96, s94, 4
	v_bfe_u32 v7, v3, 2, 1
	v_lshrrev_b32_e32 v6, 3, v3
	v_and_b32_e32 v10, 3, v3
	v_lshlrev_b32_e32 v7, 10, v7
	v_lshl_add_u32 v7, v6, 2, v7
	v_add_u32_e32 v7, v7, v10
	v_add_u32_e32 v7, s96, v7
	v_lshlrev_b32_e32 v7, 2, v7
	v_lshl_add_u32 v80, v4, 16, v7
	global_load_dword v84, v80, s[86:87]
	s_add_u32 s90, s86, 0x2000
	s_addc_u32 s91, s87, 0
	global_load_dword v85, v80, s[90:91]
	s_add_u32 s90, s86, 0x4000
	s_addc_u32 s91, s87, 0
	global_load_dword v86, v80, s[90:91]
	s_add_u32 s90, s86, 0x6000
	s_addc_u32 s91, s87, 0
	global_load_dword v87, v80, s[90:91]
	s_add_u32 s90, s86, 0x8000
	s_addc_u32 s91, s87, 0
	global_load_dword v88, v80, s[90:91]
	s_add_u32 s90, s86, 0xa000
	s_addc_u32 s91, s87, 0
	global_load_dword v89, v80, s[90:91]
	s_add_u32 s90, s86, 0xc000
	s_addc_u32 s91, s87, 0
	global_load_dword v90, v80, s[90:91]
	s_add_u32 s90, s86, 0xe000
	s_addc_u32 s91, s87, 0
	global_load_dword v91, v80, s[90:91]
	s_add_u32 s90, s86, 0x20000
	s_addc_u32 s91, s87, 0
	global_load_dword v92, v80, s[90:91]
	s_add_u32 s90, s86, 0x22000
	s_addc_u32 s91, s87, 0
	global_load_dword v93, v80, s[90:91]
	s_add_u32 s90, s86, 0x24000
	s_addc_u32 s91, s87, 0
	global_load_dword v94, v80, s[90:91]
	s_add_u32 s90, s86, 0x26000
	s_addc_u32 s91, s87, 0
	global_load_dword v95, v80, s[90:91]
	s_add_u32 s90, s86, 0x28000
	s_addc_u32 s91, s87, 0
	global_load_dword v96, v80, s[90:91]
	s_add_u32 s90, s86, 0x2a000
	s_addc_u32 s91, s87, 0
	global_load_dword v97, v80, s[90:91]
	s_add_u32 s90, s86, 0x2c000
	s_addc_u32 s91, s87, 0
	global_load_dword v98, v80, s[90:91]
	s_add_u32 s90, s86, 0x2e000
	s_addc_u32 s91, s87, 0
	global_load_dword v99, v80, s[90:91]
	s_add_u32 s90, s86, 0x40000
	s_addc_u32 s91, s87, 0
	global_load_dword v100, v80, s[90:91]
	s_add_u32 s90, s86, 0x42000
	s_addc_u32 s91, s87, 0
	global_load_dword v101, v80, s[90:91]
	s_add_u32 s90, s86, 0x44000
	s_addc_u32 s91, s87, 0
	global_load_dword v102, v80, s[90:91]
	s_add_u32 s90, s86, 0x46000
	s_addc_u32 s91, s87, 0
	global_load_dword v103, v80, s[90:91]
	s_add_u32 s90, s86, 0x48000
	s_addc_u32 s91, s87, 0
	global_load_dword v104, v80, s[90:91]
	s_add_u32 s90, s86, 0x4a000
	s_addc_u32 s91, s87, 0
	global_load_dword v105, v80, s[90:91]
	s_add_u32 s90, s86, 0x4c000
	s_addc_u32 s91, s87, 0
	global_load_dword v106, v80, s[90:91]
	s_add_u32 s90, s86, 0x4e000
	s_addc_u32 s91, s87, 0
	global_load_dword v107, v80, s[90:91]
	s_add_u32 s90, s86, 0x60000
	s_addc_u32 s91, s87, 0
	global_load_dword v108, v80, s[90:91]
	s_add_u32 s90, s86, 0x62000
	s_addc_u32 s91, s87, 0
	global_load_dword v109, v80, s[90:91]
	s_add_u32 s90, s86, 0x64000
	s_addc_u32 s91, s87, 0
	global_load_dword v110, v80, s[90:91]
	s_add_u32 s90, s86, 0x66000
	s_addc_u32 s91, s87, 0
	global_load_dword v111, v80, s[90:91]
	s_add_u32 s90, s86, 0x68000
	s_addc_u32 s91, s87, 0
	global_load_dword v76, v80, s[90:91]
	s_add_u32 s90, s86, 0x6a000
	s_addc_u32 s91, s87, 0
	global_load_dword v77, v80, s[90:91]
	s_add_u32 s90, s86, 0x6c000
	s_addc_u32 s91, s87, 0
	global_load_dword v78, v80, s[90:91]
	s_add_u32 s90, s86, 0x6e000
	s_addc_u32 s91, s87, 0
	global_load_dword v79, v80, s[90:91]
	s_lshr_b32 s72, s92, 1
	s_and_b32 s73, s92, 1
	s_lshl_b32 s55, s95, 14
	s_lshl_b32 s76, s72, 12
	s_add_i32 s55, s55, s76
	s_lshl_b32 s76, s73, 19
	s_add_i32 s55, s55, s76
	s_add_u32 s78, s66, 0x1a80000
	s_addc_u32 s79, s67, 0
	s_add_u32 s78, s78, s55
	s_addc_u32 s79, s79, 0
	s_lshl_b32 s76, s72, 13
	s_lshl_b32 s77, s73, 12
	s_add_i32 s76, s76, s77
	v_lshrrev_b32_e32 v6, 3, v2
	v_and_b32_e32 v7, 7, v2
	v_and_b32_e32 v10, 7, v6
	v_xor_b32_e32 v7, v7, v10
	v_lshlrev_b32_e32 v7, 4, v7
	v_lshl_add_u32 v81, v6, 7, v7
	s_add_i32 m0, s76, 0x0
	s_nop 0
	global_load_lds_dwordx4 v81, s[78:79]
	s_add_i32 m0, s76, 0x400
	s_add_u32 s78, s78, 0x400
	s_addc_u32 s79, s79, 0
	global_load_lds_dwordx4 v81, s[78:79]
	s_add_i32 m0, s76, 0x800
	s_add_u32 s78, s78, 0x400
	s_addc_u32 s79, s79, 0
	global_load_lds_dwordx4 v81, s[78:79]
	s_add_i32 m0, s76, 0xc00
	s_add_u32 s78, s78, 0x400
	s_addc_u32 s79, s79, 0
	global_load_lds_dwordx4 v81, s[78:79]
	v_and_b32_e32 v6, 7, v3
	v_add_u32_e32 v7, 0, v4
	v_xor_b32_e32 v7, v7, v6
	v_lshlrev_b32_e32 v7, 4, v7
	v_lshl_add_u32 v48, v3, 7, v7
	v_add_u32_e32 v7, 2, v4
	v_xor_b32_e32 v7, v7, v6
	v_lshlrev_b32_e32 v7, 4, v7
	v_lshl_add_u32 v49, v3, 7, v7
	v_add_u32_e32 v7, 4, v4
	v_xor_b32_e32 v7, v7, v6
	v_lshlrev_b32_e32 v7, 4, v7
	v_lshl_add_u32 v50, v3, 7, v7
	v_add_u32_e32 v7, 6, v4
	v_xor_b32_e32 v7, v7, v6
	v_lshlrev_b32_e32 v7, 4, v7
	v_lshl_add_u32 v51, v3, 7, v7
	s_lshl_b32 s55, s96, 14
	s_add_u32 s84, s66, 0x9c00000
	s_addc_u32 s85, s67, 0
	s_add_u32 s84, s84, s55
	s_addc_u32 s85, s85, 0
	v_and_b32_e32 v6, 15, v2
	v_add_u32_e32 v6, s96, v6
	v_cvt_f32_u32_e32 v6, v6
	v_div_scale_f32 v7, s[16:17], s61, s61, v6
	v_rcp_f32_e32 v12, v7
	v_div_scale_f32 v13, vcc, v6, s61, v6
	v_fma_f32 v10, -v7, v12, 1.0
	v_fmac_f32_e32 v12, v10, v12
	v_mul_f32_e32 v10, v13, v12
	v_fma_f32 v11, -v7, v10, v13
	v_fmac_f32_e32 v10, v11, v12
	v_fma_f32 v7, -v7, v10, v13
	s_nop 1
	v_div_fmas_f32 v7, v7, v12, v10
	v_div_fixup_f32 v6, v7, s61, v6
	v_mov_b32_e32 v7, 0xc0447cbd
	v_fmamk_f32 v6, v6, 0xc1447cbd, v7
	v_and_b32_e32 v6, 0x7fffffff, v6
	s_nop 0
	v_readlane_b32 s6, v6, 0
	v_readlane_b32 s7, v6, 1
	v_readlane_b32 s10, v6, 2
	v_readlane_b32 s11, v6, 3
	v_readlane_b32 s24, v6, 4
	v_readlane_b32 s26, v6, 5
	v_readlane_b32 s32, v6, 6
	v_readlane_b32 s35, v6, 7
	v_readlane_b32 s41, v6, 8
	v_readlane_b32 s44, v6, 9
	v_readlane_b32 s45, v6, 10
	v_readlane_b32 s47, v6, 11
	v_readlane_b32 s48, v6, 12
	v_readlane_b32 s49, v6, 13
	v_readlane_b32 s52, v6, 14
	v_readlane_b32 s53, v6, 15
	s_waitcnt vmcnt(0)
	v_cvt_pk_bf16_f32 v6, v84, v85
	v_lshlrev_b32_e32 v12, 16, v6
	v_and_b32_e32 v13, 0xffff0000, v6
	v_sub_f32_e32 v84, v84, v12
	v_sub_f32_e32 v85, v85, v13
	v_cvt_pk_bf16_f32 v70, v84, v85
	v_cvt_pk_bf16_f32 v7, v86, v87
	v_lshlrev_b32_e32 v12, 16, v7
	v_and_b32_e32 v13, 0xffff0000, v7
	v_sub_f32_e32 v86, v86, v12
	v_sub_f32_e32 v87, v87, v13
	v_cvt_pk_bf16_f32 v71, v86, v87
	v_cvt_pk_bf16_f32 v10, v88, v89
	v_lshlrev_b32_e32 v12, 16, v10
	v_and_b32_e32 v13, 0xffff0000, v10
	v_sub_f32_e32 v88, v88, v12
	v_sub_f32_e32 v89, v89, v13
	v_cvt_pk_bf16_f32 v72, v88, v89
	v_cvt_pk_bf16_f32 v11, v90, v91
	v_lshlrev_b32_e32 v12, 16, v11
	v_and_b32_e32 v13, 0xffff0000, v11
	v_sub_f32_e32 v90, v90, v12
	v_sub_f32_e32 v91, v91, v13
	v_cvt_pk_bf16_f32 v73, v90, v91
	v_mov_b32_e32 v84, v6
	v_mov_b32_e32 v88, v70
	v_mov_b32_e32 v85, v7
	v_mov_b32_e32 v89, v71
	v_mov_b32_e32 v86, v10
	v_mov_b32_e32 v90, v72
	v_mov_b32_e32 v87, v11
	v_mov_b32_e32 v91, v73
	v_cvt_pk_bf16_f32 v6, v92, v93
	v_lshlrev_b32_e32 v12, 16, v6
	v_and_b32_e32 v13, 0xffff0000, v6
	v_sub_f32_e32 v92, v92, v12
	v_sub_f32_e32 v93, v93, v13
	v_cvt_pk_bf16_f32 v70, v92, v93
	v_cvt_pk_bf16_f32 v7, v94, v95
	v_lshlrev_b32_e32 v12, 16, v7
	v_and_b32_e32 v13, 0xffff0000, v7
	v_sub_f32_e32 v94, v94, v12
	v_sub_f32_e32 v95, v95, v13
	v_cvt_pk_bf16_f32 v71, v94, v95
	v_cvt_pk_bf16_f32 v10, v96, v97
	v_lshlrev_b32_e32 v12, 16, v10
	v_and_b32_e32 v13, 0xffff0000, v10
	v_sub_f32_e32 v96, v96, v12
	v_sub_f32_e32 v97, v97, v13
	v_cvt_pk_bf16_f32 v72, v96, v97
	v_cvt_pk_bf16_f32 v11, v98, v99
	v_lshlrev_b32_e32 v12, 16, v11
	v_and_b32_e32 v13, 0xffff0000, v11
	v_sub_f32_e32 v98, v98, v12
	v_sub_f32_e32 v99, v99, v13
	v_cvt_pk_bf16_f32 v73, v98, v99
	v_mov_b32_e32 v92, v6
	v_mov_b32_e32 v96, v70
	v_mov_b32_e32 v93, v7
	v_mov_b32_e32 v97, v71
	v_mov_b32_e32 v94, v10
	v_mov_b32_e32 v98, v72
	v_mov_b32_e32 v95, v11
	v_mov_b32_e32 v99, v73
	v_cvt_pk_bf16_f32 v6, v100, v101
	v_lshlrev_b32_e32 v12, 16, v6
	v_and_b32_e32 v13, 0xffff0000, v6
	v_sub_f32_e32 v100, v100, v12
	v_sub_f32_e32 v101, v101, v13
	v_cvt_pk_bf16_f32 v70, v100, v101
	v_cvt_pk_bf16_f32 v7, v102, v103
	v_lshlrev_b32_e32 v12, 16, v7
	v_and_b32_e32 v13, 0xffff0000, v7
	v_sub_f32_e32 v102, v102, v12
	v_sub_f32_e32 v103, v103, v13
	v_cvt_pk_bf16_f32 v71, v102, v103
	v_cvt_pk_bf16_f32 v10, v104, v105
	v_lshlrev_b32_e32 v12, 16, v10
	v_and_b32_e32 v13, 0xffff0000, v10
	v_sub_f32_e32 v104, v104, v12
	v_sub_f32_e32 v105, v105, v13
	v_cvt_pk_bf16_f32 v72, v104, v105
	v_cvt_pk_bf16_f32 v11, v106, v107
	v_lshlrev_b32_e32 v12, 16, v11
	v_and_b32_e32 v13, 0xffff0000, v11
	v_sub_f32_e32 v106, v106, v12
	v_sub_f32_e32 v107, v107, v13
	v_cvt_pk_bf16_f32 v73, v106, v107
	v_mov_b32_e32 v100, v6
	v_mov_b32_e32 v104, v70
	v_mov_b32_e32 v101, v7
	v_mov_b32_e32 v105, v71
	v_mov_b32_e32 v102, v10
	v_mov_b32_e32 v106, v72
	v_mov_b32_e32 v103, v11
	v_mov_b32_e32 v107, v73
	v_cvt_pk_bf16_f32 v6, v108, v109
	v_lshlrev_b32_e32 v12, 16, v6
	v_and_b32_e32 v13, 0xffff0000, v6
	v_sub_f32_e32 v108, v108, v12
	v_sub_f32_e32 v109, v109, v13
	v_cvt_pk_bf16_f32 v70, v108, v109
	v_cvt_pk_bf16_f32 v7, v110, v111
	v_lshlrev_b32_e32 v12, 16, v7
	v_and_b32_e32 v13, 0xffff0000, v7
	v_sub_f32_e32 v110, v110, v12
	v_sub_f32_e32 v111, v111, v13
	v_cvt_pk_bf16_f32 v71, v110, v111
	v_cvt_pk_bf16_f32 v10, v76, v77
	v_lshlrev_b32_e32 v12, 16, v10
	v_and_b32_e32 v13, 0xffff0000, v10
	v_sub_f32_e32 v76, v76, v12
	v_sub_f32_e32 v77, v77, v13
	v_cvt_pk_bf16_f32 v72, v76, v77
	v_cvt_pk_bf16_f32 v11, v78, v79
	v_lshlrev_b32_e32 v12, 16, v11
	v_and_b32_e32 v13, 0xffff0000, v11
	v_sub_f32_e32 v78, v78, v12
	v_sub_f32_e32 v79, v79, v13
	v_cvt_pk_bf16_f32 v73, v78, v79
	v_mov_b32_e32 v108, v6
	v_mov_b32_e32 v76, v70
	v_mov_b32_e32 v109, v7
	v_mov_b32_e32 v77, v71
	v_mov_b32_e32 v110, v10
	v_mov_b32_e32 v78, v72
	v_mov_b32_e32 v111, v11
	v_mov_b32_e32 v79, v73
	s_lshl_b32 s55, s95, 7
	s_barrier
	ds_read_b128 v[112:115], v48 offset:0
	ds_read_b128 v[116:119], v49 offset:0
	ds_read_b128 v[120:123], v50 offset:0
	ds_read_b128 v[124:127], v51 offset:0
	ds_read_b128 v[128:131], v48 offset:4096
	ds_read_b128 v[132:135], v49 offset:4096
	ds_read_b128 v[136:139], v50 offset:4096
	ds_read_b128 v[140:143], v51 offset:4096
	s_waitcnt lgkmcnt(0)
	s_nop 1
	ds_read_b128 v[144:147], v48 offset:8192
	ds_read_b128 v[148:151], v49 offset:8192
	ds_read_b128 v[152:155], v50 offset:8192
	ds_read_b128 v[156:159], v51 offset:8192
	ds_read_b128 v[160:163], v48 offset:12288
	ds_read_b128 v[164:167], v49 offset:12288
	ds_read_b128 v[168:171], v50 offset:12288
	ds_read_b128 v[172:175], v51 offset:12288
	v_mfma_f32_32x32x16_bf16 v[14:29], v[84:87], v[112:115], 0
	v_mfma_f32_32x32x16_bf16 v[14:29], v[84:87], v[128:131], v[14:29]
	v_mfma_f32_32x32x16_bf16 v[14:29], v[88:91], v[112:115], v[14:29]
	v_mfma_f32_32x32x16_bf16 v[14:29], v[92:95], v[116:119], v[14:29]
	v_mfma_f32_32x32x16_bf16 v[14:29], v[92:95], v[132:135], v[14:29]
	v_mfma_f32_32x32x16_bf16 v[14:29], v[96:99], v[116:119], v[14:29]
	v_mfma_f32_32x32x16_bf16 v[14:29], v[100:103], v[120:123], v[14:29]
	v_mfma_f32_32x32x16_bf16 v[14:29], v[100:103], v[136:139], v[14:29]
	v_mfma_f32_32x32x16_bf16 v[14:29], v[104:107], v[120:123], v[14:29]
	v_mfma_f32_32x32x16_bf16 v[14:29], v[108:111], v[124:127], v[14:29]
	v_mfma_f32_32x32x16_bf16 v[14:29], v[108:111], v[140:143], v[14:29]
	v_mfma_f32_32x32x16_bf16 v[14:29], v[76:79], v[124:127], v[14:29]
	s_waitcnt lgkmcnt(0)
	ds_read_b128 v[112:115], v48 offset:16384
	ds_read_b128 v[116:119], v49 offset:16384
	ds_read_b128 v[120:123], v50 offset:16384
	ds_read_b128 v[124:127], v51 offset:16384
	ds_read_b128 v[128:131], v48 offset:20480
	ds_read_b128 v[132:135], v49 offset:20480
	ds_read_b128 v[136:139], v50 offset:20480
	ds_read_b128 v[140:143], v51 offset:20480
	v_mfma_f32_32x32x16_bf16 v[32:47], v[84:87], v[144:147], 0
	v_add_u32_e32 v70, s55, v3
	v_cvt_f32_i32_e32 v71, v70
	v_mul_f32_e32 v71, 0xb9b8b5c6, v71
	v_sub_u32_e32 v72, 0x1000, v70
	v_add_u32_e32 v73, 0x1000, v70
	v_cmp_eq_u32_e32 vcc, 0, v70
	s_and_b64 s[16:17], vcc, s[14:15]
	s_andn2_b64 s[18:19], vcc, s[14:15]
	v_cndmask_b32_e64 v73, v73, 0, vcc
	v_cndmask_b32_e64 v72, v72, v73, s[14:15]
	v_lshlrev_b32_e32 v72, 1, v72
	s_mov_b64 s[90:91], s[84:85]
	s_add_i32 s55, s55, 32
	s_cmp_lg_u32 s95, 0
	s_cbranch_scc1 .Lpf_noskip
	s_lshl_b32 s72, s96, 2
	s_add_u32 s72, s88, s72
	s_addc_u32 s73, s89, 0
	global_load_dwordx4 v[176:179], v82, s[72:73]
	global_load_dwordx4 v[180:183], v82, s[72:73] offset:16
	global_load_dwordx4 v[184:187], v82, s[72:73] offset:32
	global_load_dwordx4 v[188:191], v82, s[72:73] offset:48
	s_waitcnt vmcnt(0)
.Lpf_noskip:
	s_nop 7
	v_mfma_f32_32x32x16_bf16 v[32:47], v[84:87], v[160:163], v[32:47]
	v_mul_f32_e32 v10, s6, v71
	v_mul_f32_e32 v11, s7, v71
	v_exp_f32_e32 v10, v10
	v_exp_f32_e32 v11, v11
	s_nop 0
	v_pk_add_f32 v[10:11], v[10:11], v[8:9]
	v_pk_mul_f32 v[10:11], v[10:11], v[14:15]
	v_add_f32_e32 v6, v176, v10
	v_cndmask_b32_e64 v10, v10, v6, s[18:19]
	v_cndmask_b32_e64 v10, v10, 0, s[16:17]
	v_add_f32_e32 v6, v177, v11
	v_cndmask_b32_e64 v11, v11, v6, s[18:19]
	v_cndmask_b32_e64 v11, v11, 0, s[16:17]
	v_cvt_pk_bf16_f32 v10, v10, v11
	global_store_short v72, v10, s[90:91]
	v_mfma_f32_32x32x16_bf16 v[32:47], v[88:91], v[144:147], v[32:47]
	s_add_u32 s90, s90, 0x4000
	s_addc_u32 s91, s91, 0
	global_store_short_d16_hi v72, v10, s[90:91]
	s_add_u32 s90, s90, 0x4000
	s_addc_u32 s91, s91, 0
	v_mul_f32_e32 v12, s10, v71
	v_mul_f32_e32 v13, s11, v71
	v_exp_f32_e32 v12, v12
	v_exp_f32_e32 v13, v13
	s_nop 0
	v_pk_add_f32 v[12:13], v[12:13], v[8:9]
	v_pk_mul_f32 v[12:13], v[12:13], v[16:17]
	v_add_f32_e32 v6, v178, v12
	v_cndmask_b32_e64 v12, v12, v6, s[18:19]
	v_cndmask_b32_e64 v12, v12, 0, s[16:17]
	v_mfma_f32_32x32x16_bf16 v[32:47], v[92:95], v[148:151], v[32:47]
	v_add_f32_e32 v6, v179, v13
	v_cndmask_b32_e64 v13, v13, v6, s[18:19]
	v_cndmask_b32_e64 v13, v13, 0, s[16:17]
	v_cvt_pk_bf16_f32 v12, v12, v13
	global_store_short v72, v12, s[90:91]
	s_add_u32 s90, s90, 0x4000
	s_addc_u32 s91, s91, 0
	global_store_short_d16_hi v72, v12, s[90:91]
	s_add_u32 s90, s90, 0x4000
	s_addc_u32 s91, s91, 0
	v_mul_f32_e32 v10, s24, v71
	v_mul_f32_e32 v11, s26, v71
	v_exp_f32_e32 v10, v10
	v_exp_f32_e32 v11, v11
	s_nop 0
	v_mfma_f32_32x32x16_bf16 v[32:47], v[92:95], v[164:167], v[32:47]
	v_pk_add_f32 v[10:11], v[10:11], v[8:9]
	v_pk_mul_f32 v[10:11], v[10:11], v[18:19]
	v_add_f32_e32 v6, v180, v10
	v_cndmask_b32_e64 v10, v10, v6, s[18:19]
	v_cndmask_b32_e64 v10, v10, 0, s[16:17]
	v_add_f32_e32 v6, v181, v11
	v_cndmask_b32_e64 v11, v11, v6, s[18:19]
	v_cndmask_b32_e64 v11, v11, 0, s[16:17]
	v_cvt_pk_bf16_f32 v10, v10, v11
	global_store_short v72, v10, s[90:91]
	s_add_u32 s90, s90, 0x4000
	s_addc_u32 s91, s91, 0
	global_store_short_d16_hi v72, v10, s[90:91]
	s_add_u32 s90, s90, 0x4000
	s_addc_u32 s91, s91, 0
	v_mfma_f32_32x32x16_bf16 v[32:47], v[96:99], v[148:151], v[32:47]
	v_mul_f32_e32 v12, s32, v71
	v_mul_f32_e32 v13, s35, v71
	v_exp_f32_e32 v12, v12
	v_exp_f32_e32 v13, v13
	s_nop 0
	v_pk_add_f32 v[12:13], v[12:13], v[8:9]
	v_pk_mul_f32 v[12:13], v[12:13], v[20:21]
	v_add_f32_e32 v6, v182, v12
	v_cndmask_b32_e64 v12, v12, v6, s[18:19]
	v_cndmask_b32_e64 v12, v12, 0, s[16:17]
	v_add_f32_e32 v6, v183, v13
	v_cndmask_b32_e64 v13, v13, v6, s[18:19]
	v_cndmask_b32_e64 v13, v13, 0, s[16:17]
	v_cvt_pk_bf16_f32 v12, v12, v13
	global_store_short v72, v12, s[90:91]
	v_mfma_f32_32x32x16_bf16 v[32:47], v[100:103], v[152:155], v[32:47]
	s_add_u32 s90, s90, 0x4000
	s_addc_u32 s91, s91, 0
	global_store_short_d16_hi v72, v12, s[90:91]
	s_add_u32 s90, s90, 0x4000
	s_addc_u32 s91, s91, 0
	v_mul_f32_e32 v10, s41, v71
	v_mul_f32_e32 v11, s44, v71
	v_exp_f32_e32 v10, v10
	v_exp_f32_e32 v11, v11
	s_nop 0
	v_pk_add_f32 v[10:11], v[10:11], v[8:9]
	v_pk_mul_f32 v[10:11], v[10:11], v[22:23]
	v_add_f32_e32 v6, v184, v10
	v_cndmask_b32_e64 v10, v10, v6, s[18:19]
	v_cndmask_b32_e64 v10, v10, 0, s[16:17]
	v_mfma_f32_32x32x16_bf16 v[32:47], v[100:103], v[168:171], v[32:47]
	v_add_f32_e32 v6, v185, v11
	v_cndmask_b32_e64 v11, v11, v6, s[18:19]
	v_cndmask_b32_e64 v11, v11, 0, s[16:17]
	v_cvt_pk_bf16_f32 v10, v10, v11
	global_store_short v72, v10, s[90:91]
	s_add_u32 s90, s90, 0x4000
	s_addc_u32 s91, s91, 0
	global_store_short_d16_hi v72, v10, s[90:91]
	s_add_u32 s90, s90, 0x4000
	s_addc_u32 s91, s91, 0
	v_mul_f32_e32 v12, s45, v71
	v_mul_f32_e32 v13, s47, v71
	v_exp_f32_e32 v12, v12
	v_exp_f32_e32 v13, v13
	s_nop 0
	v_mfma_f32_32x32x16_bf16 v[32:47], v[104:107], v[152:155], v[32:47]
	v_pk_add_f32 v[12:13], v[12:13], v[8:9]
	v_pk_mul_f32 v[12:13], v[12:13], v[24:25]
	v_add_f32_e32 v6, v186, v12
	v_cndmask_b32_e64 v12, v12, v6, s[18:19]
	v_cndmask_b32_e64 v12, v12, 0, s[16:17]
	v_add_f32_e32 v6, v187, v13
	v_cndmask_b32_e64 v13, v13, v6, s[18:19]
	v_cndmask_b32_e64 v13, v13, 0, s[16:17]
	v_cvt_pk_bf16_f32 v12, v12, v13
	global_store_short v72, v12, s[90:91]
	s_add_u32 s90, s90, 0x4000
	s_addc_u32 s91, s91, 0
	global_store_short_d16_hi v72, v12, s[90:91]
	s_add_u32 s90, s90, 0x4000
	s_addc_u32 s91, s91, 0
	v_mfma_f32_32x32x16_bf16 v[32:47], v[108:111], v[156:159], v[32:47]
	v_mul_f32_e32 v10, s48, v71
	v_mul_f32_e32 v11, s49, v71
	v_exp_f32_e32 v10, v10
	v_exp_f32_e32 v11, v11
	s_nop 0
	v_pk_add_f32 v[10:11], v[10:11], v[8:9]
	v_pk_mul_f32 v[10:11], v[10:11], v[26:27]
	v_add_f32_e32 v6, v188, v10
	v_cndmask_b32_e64 v10, v10, v6, s[18:19]
	v_cndmask_b32_e64 v10, v10, 0, s[16:17]
	v_add_f32_e32 v6, v189, v11
	v_cndmask_b32_e64 v11, v11, v6, s[18:19]
	v_cndmask_b32_e64 v11, v11, 0, s[16:17]
	v_cvt_pk_bf16_f32 v10, v10, v11
	global_store_short v72, v10, s[90:91]
	v_mfma_f32_32x32x16_bf16 v[32:47], v[108:111], v[172:175], v[32:47]
	s_add_u32 s90, s90, 0x4000
	s_addc_u32 s91, s91, 0
	global_store_short_d16_hi v72, v10, s[90:91]
	s_add_u32 s90, s90, 0x4000
	s_addc_u32 s91, s91, 0
	v_mul_f32_e32 v12, s52, v71
	v_mul_f32_e32 v13, s53, v71
	v_exp_f32_e32 v12, v12
	v_exp_f32_e32 v13, v13
	s_nop 0
	v_pk_add_f32 v[12:13], v[12:13], v[8:9]
	v_pk_mul_f32 v[12:13], v[12:13], v[28:29]
	v_add_f32_e32 v6, v190, v12
	v_cndmask_b32_e64 v12, v12, v6, s[18:19]
	v_cndmask_b32_e64 v12, v12, 0, s[16:17]
	v_mfma_f32_32x32x16_bf16 v[32:47], v[76:79], v[156:159], v[32:47]
	v_add_f32_e32 v6, v191, v13
	v_cndmask_b32_e64 v13, v13, v6, s[18:19]
	v_cndmask_b32_e64 v13, v13, 0, s[16:17]
	v_cvt_pk_bf16_f32 v12, v12, v13
	global_store_short v72, v12, s[90:91]
	s_add_u32 s90, s90, 0x4000
	s_addc_u32 s91, s91, 0
	global_store_short_d16_hi v72, v12, s[90:91]
	s_waitcnt lgkmcnt(0)
	ds_read_b128 v[144:147], v48 offset:24576
	ds_read_b128 v[148:151], v49 offset:24576
	ds_read_b128 v[152:155], v50 offset:24576
	ds_read_b128 v[156:159], v51 offset:24576
	ds_read_b128 v[160:163], v48 offset:28672
	ds_read_b128 v[164:167], v49 offset:28672
	ds_read_b128 v[168:171], v50 offset:28672
	ds_read_b128 v[172:175], v51 offset:28672
	v_mfma_f32_32x32x16_bf16 v[14:29], v[84:87], v[112:115], 0
	v_add_u32_e32 v70, s55, v3
	v_cvt_f32_i32_e32 v71, v70
	v_mul_f32_e32 v71, 0xb9b8b5c6, v71
	v_sub_u32_e32 v72, 0x1000, v70
	v_add_u32_e32 v73, 0x1000, v70
	v_cndmask_b32_e64 v72, v72, v73, s[14:15]
	v_lshlrev_b32_e32 v72, 1, v72
	s_mov_b64 s[90:91], s[84:85]
	s_add_i32 s55, s55, 32
	s_nop 7
	v_mfma_f32_32x32x16_bf16 v[14:29], v[84:87], v[128:131], v[14:29]
	v_mul_f32_e32 v10, s6, v71
	v_mul_f32_e32 v11, s7, v71
	v_exp_f32_e32 v10, v10
	v_exp_f32_e32 v11, v11
	s_nop 0
	v_pk_add_f32 v[10:11], v[10:11], v[8:9]
	v_pk_mul_f32 v[10:11], v[10:11], v[32:33]
	v_cvt_pk_bf16_f32 v10, v10, v11
	global_store_short v72, v10, s[90:91]
	s_add_u32 s90, s90, 0x4000
	v_mfma_f32_32x32x16_bf16 v[14:29], v[88:91], v[112:115], v[14:29]
	s_addc_u32 s91, s91, 0
	global_store_short_d16_hi v72, v10, s[90:91]
	s_add_u32 s90, s90, 0x4000
	s_addc_u32 s91, s91, 0
	v_mul_f32_e32 v12, s10, v71
	v_mul_f32_e32 v13, s11, v71
	v_exp_f32_e32 v12, v12
	v_exp_f32_e32 v13, v13
	s_nop 0
	v_pk_add_f32 v[12:13], v[12:13], v[8:9]
	v_mfma_f32_32x32x16_bf16 v[14:29], v[92:95], v[116:119], v[14:29]
	v_pk_mul_f32 v[12:13], v[12:13], v[34:35]
	v_cvt_pk_bf16_f32 v12, v12, v13
	global_store_short v72, v12, s[90:91]
	s_add_u32 s90, s90, 0x4000
	s_addc_u32 s91, s91, 0
	global_store_short_d16_hi v72, v12, s[90:91]
	s_add_u32 s90, s90, 0x4000
	s_addc_u32 s91, s91, 0
	v_mul_f32_e32 v10, s24, v71
	v_mul_f32_e32 v11, s26, v71
	v_mfma_f32_32x32x16_bf16 v[14:29], v[92:95], v[132:135], v[14:29]
	v_exp_f32_e32 v10, v10
	v_exp_f32_e32 v11, v11
	s_nop 0
	v_pk_add_f32 v[10:11], v[10:11], v[8:9]
	v_pk_mul_f32 v[10:11], v[10:11], v[36:37]
	v_cvt_pk_bf16_f32 v10, v10, v11
	global_store_short v72, v10, s[90:91]
	s_add_u32 s90, s90, 0x4000
	s_addc_u32 s91, s91, 0
	global_store_short_d16_hi v72, v10, s[90:91]
	v_mfma_f32_32x32x16_bf16 v[14:29], v[96:99], v[116:119], v[14:29]
	s_add_u32 s90, s90, 0x4000
	s_addc_u32 s91, s91, 0
	v_mul_f32_e32 v12, s32, v71
	v_mul_f32_e32 v13, s35, v71
	v_exp_f32_e32 v12, v12
	v_exp_f32_e32 v13, v13
	s_nop 0
	v_pk_add_f32 v[12:13], v[12:13], v[8:9]
	v_pk_mul_f32 v[12:13], v[12:13], v[38:39]
	v_cvt_pk_bf16_f32 v12, v12, v13
	v_mfma_f32_32x32x16_bf16 v[14:29], v[100:103], v[120:123], v[14:29]
	global_store_short v72, v12, s[90:91]
	s_add_u32 s90, s90, 0x4000
	s_addc_u32 s91, s91, 0
	global_store_short_d16_hi v72, v12, s[90:91]
	s_add_u32 s90, s90, 0x4000
	s_addc_u32 s91, s91, 0
	v_mul_f32_e32 v10, s41, v71
	v_mul_f32_e32 v11, s44, v71
	v_exp_f32_e32 v10, v10
	v_exp_f32_e32 v11, v11
	v_mfma_f32_32x32x16_bf16 v[14:29], v[100:103], v[136:139], v[14:29]
	s_nop 0
	v_pk_add_f32 v[10:11], v[10:11], v[8:9]
	v_pk_mul_f32 v[10:11], v[10:11], v[40:41]
	v_cvt_pk_bf16_f32 v10, v10, v11
	global_store_short v72, v10, s[90:91]
	s_add_u32 s90, s90, 0x4000
	s_addc_u32 s91, s91, 0
	global_store_short_d16_hi v72, v10, s[90:91]
	s_add_u32 s90, s90, 0x4000
	s_addc_u32 s91, s91, 0
	v_mfma_f32_32x32x16_bf16 v[14:29], v[104:107], v[120:123], v[14:29]
	v_mul_f32_e32 v12, s45, v71
	v_mul_f32_e32 v13, s47, v71
	v_exp_f32_e32 v12, v12
	v_exp_f32_e32 v13, v13
	s_nop 0
	v_pk_add_f32 v[12:13], v[12:13], v[8:9]
	v_pk_mul_f32 v[12:13], v[12:13], v[42:43]
	v_cvt_pk_bf16_f32 v12, v12, v13
	global_store_short v72, v12, s[90:91]
	s_add_u32 s90, s90, 0x4000
	v_mfma_f32_32x32x16_bf16 v[14:29], v[108:111], v[124:127], v[14:29]
	s_addc_u32 s91, s91, 0
	global_store_short_d16_hi v72, v12, s[90:91]
	s_add_u32 s90, s90, 0x4000
	s_addc_u32 s91, s91, 0
	v_mul_f32_e32 v10, s48, v71
	v_mul_f32_e32 v11, s49, v71
	v_exp_f32_e32 v10, v10
	v_exp_f32_e32 v11, v11
	s_nop 0
	v_pk_add_f32 v[10:11], v[10:11], v[8:9]
	v_mfma_f32_32x32x16_bf16 v[14:29], v[108:111], v[140:143], v[14:29]
	v_pk_mul_f32 v[10:11], v[10:11], v[44:45]
	v_cvt_pk_bf16_f32 v10, v10, v11
	global_store_short v72, v10, s[90:91]
	s_add_u32 s90, s90, 0x4000
	s_addc_u32 s91, s91, 0
	global_store_short_d16_hi v72, v10, s[90:91]
	s_add_u32 s90, s90, 0x4000
	s_addc_u32 s91, s91, 0
	v_mul_f32_e32 v12, s52, v71
	v_mul_f32_e32 v13, s53, v71
	v_mfma_f32_32x32x16_bf16 v[14:29], v[76:79], v[124:127], v[14:29]
	v_exp_f32_e32 v12, v12
	v_exp_f32_e32 v13, v13
	s_nop 0
	v_pk_add_f32 v[12:13], v[12:13], v[8:9]
	v_pk_mul_f32 v[12:13], v[12:13], v[46:47]
	v_cvt_pk_bf16_f32 v12, v12, v13
	global_store_short v72, v12, s[90:91]
	s_add_u32 s90, s90, 0x4000
	s_addc_u32 s91, s91, 0
	global_store_short_d16_hi v72, v12, s[90:91]
	s_waitcnt lgkmcnt(0)
	v_mfma_f32_32x32x16_bf16 v[32:47], v[84:87], v[144:147], 0
	v_add_u32_e32 v70, s55, v3
	v_cvt_f32_i32_e32 v71, v70
	v_mul_f32_e32 v71, 0xb9b8b5c6, v71
	v_sub_u32_e32 v72, 0x1000, v70
	v_add_u32_e32 v73, 0x1000, v70
	v_cndmask_b32_e64 v72, v72, v73, s[14:15]
	v_lshlrev_b32_e32 v72, 1, v72
	s_mov_b64 s[90:91], s[84:85]
	s_add_i32 s55, s55, 32
	s_nop 7
	v_mfma_f32_32x32x16_bf16 v[32:47], v[84:87], v[160:163], v[32:47]
	v_mul_f32_e32 v10, s6, v71
	v_mul_f32_e32 v11, s7, v71
	v_exp_f32_e32 v10, v10
	v_exp_f32_e32 v11, v11
	s_nop 0
	v_pk_add_f32 v[10:11], v[10:11], v[8:9]
	v_pk_mul_f32 v[10:11], v[10:11], v[14:15]
	v_cvt_pk_bf16_f32 v10, v10, v11
	global_store_short v72, v10, s[90:91]
	s_add_u32 s90, s90, 0x4000
	v_mfma_f32_32x32x16_bf16 v[32:47], v[88:91], v[144:147], v[32:47]
	s_addc_u32 s91, s91, 0
	global_store_short_d16_hi v72, v10, s[90:91]
	s_add_u32 s90, s90, 0x4000
	s_addc_u32 s91, s91, 0
	v_mul_f32_e32 v12, s10, v71
	v_mul_f32_e32 v13, s11, v71
	v_exp_f32_e32 v12, v12
	v_exp_f32_e32 v13, v13
	s_nop 0
	v_pk_add_f32 v[12:13], v[12:13], v[8:9]
	v_mfma_f32_32x32x16_bf16 v[32:47], v[92:95], v[148:151], v[32:47]
	v_pk_mul_f32 v[12:13], v[12:13], v[16:17]
	v_cvt_pk_bf16_f32 v12, v12, v13
	global_store_short v72, v12, s[90:91]
	s_add_u32 s90, s90, 0x4000
	s_addc_u32 s91, s91, 0
	global_store_short_d16_hi v72, v12, s[90:91]
	s_add_u32 s90, s90, 0x4000
	s_addc_u32 s91, s91, 0
	v_mul_f32_e32 v10, s24, v71
	v_mul_f32_e32 v11, s26, v71
	v_mfma_f32_32x32x16_bf16 v[32:47], v[92:95], v[164:167], v[32:47]
	v_exp_f32_e32 v10, v10
	v_exp_f32_e32 v11, v11
	s_nop 0
	v_pk_add_f32 v[10:11], v[10:11], v[8:9]
	v_pk_mul_f32 v[10:11], v[10:11], v[18:19]
	v_cvt_pk_bf16_f32 v10, v10, v11
	global_store_short v72, v10, s[90:91]
	s_add_u32 s90, s90, 0x4000
	s_addc_u32 s91, s91, 0
	global_store_short_d16_hi v72, v10, s[90:91]
	v_mfma_f32_32x32x16_bf16 v[32:47], v[96:99], v[148:151], v[32:47]
	s_add_u32 s90, s90, 0x4000
	s_addc_u32 s91, s91, 0
	v_mul_f32_e32 v12, s32, v71
	v_mul_f32_e32 v13, s35, v71
	v_exp_f32_e32 v12, v12
	v_exp_f32_e32 v13, v13
	s_nop 0
	v_pk_add_f32 v[12:13], v[12:13], v[8:9]
	v_pk_mul_f32 v[12:13], v[12:13], v[20:21]
	v_cvt_pk_bf16_f32 v12, v12, v13
	v_mfma_f32_32x32x16_bf16 v[32:47], v[100:103], v[152:155], v[32:47]
	global_store_short v72, v12, s[90:91]
	s_add_u32 s90, s90, 0x4000
	s_addc_u32 s91, s91, 0
	global_store_short_d16_hi v72, v12, s[90:91]
	s_add_u32 s90, s90, 0x4000
	s_addc_u32 s91, s91, 0
	v_mul_f32_e32 v10, s41, v71
	v_mul_f32_e32 v11, s44, v71
	v_exp_f32_e32 v10, v10
	v_exp_f32_e32 v11, v11
	v_mfma_f32_32x32x16_bf16 v[32:47], v[100:103], v[168:171], v[32:47]
	s_nop 0
	v_pk_add_f32 v[10:11], v[10:11], v[8:9]
	v_pk_mul_f32 v[10:11], v[10:11], v[22:23]
	v_cvt_pk_bf16_f32 v10, v10, v11
	global_store_short v72, v10, s[90:91]
	s_add_u32 s90, s90, 0x4000
	s_addc_u32 s91, s91, 0
	global_store_short_d16_hi v72, v10, s[90:91]
	s_add_u32 s90, s90, 0x4000
	s_addc_u32 s91, s91, 0
	v_mfma_f32_32x32x16_bf16 v[32:47], v[104:107], v[152:155], v[32:47]
	v_mul_f32_e32 v12, s45, v71
	v_mul_f32_e32 v13, s47, v71
	v_exp_f32_e32 v12, v12
	v_exp_f32_e32 v13, v13
	s_nop 0
	v_pk_add_f32 v[12:13], v[12:13], v[8:9]
	v_pk_mul_f32 v[12:13], v[12:13], v[24:25]
	v_cvt_pk_bf16_f32 v12, v12, v13
	global_store_short v72, v12, s[90:91]
	s_add_u32 s90, s90, 0x4000
	v_mfma_f32_32x32x16_bf16 v[32:47], v[108:111], v[156:159], v[32:47]
	s_addc_u32 s91, s91, 0
	global_store_short_d16_hi v72, v12, s[90:91]
	s_add_u32 s90, s90, 0x4000
	s_addc_u32 s91, s91, 0
	v_mul_f32_e32 v10, s48, v71
	v_mul_f32_e32 v11, s49, v71
	v_exp_f32_e32 v10, v10
	v_exp_f32_e32 v11, v11
	s_nop 0
	v_pk_add_f32 v[10:11], v[10:11], v[8:9]
	v_mfma_f32_32x32x16_bf16 v[32:47], v[108:111], v[172:175], v[32:47]
	v_pk_mul_f32 v[10:11], v[10:11], v[26:27]
	v_cvt_pk_bf16_f32 v10, v10, v11
	global_store_short v72, v10, s[90:91]
	s_add_u32 s90, s90, 0x4000
	s_addc_u32 s91, s91, 0
	global_store_short_d16_hi v72, v10, s[90:91]
	s_add_u32 s90, s90, 0x4000
	s_addc_u32 s91, s91, 0
	v_mul_f32_e32 v12, s52, v71
	v_mul_f32_e32 v13, s53, v71
	v_mfma_f32_32x32x16_bf16 v[32:47], v[76:79], v[156:159], v[32:47]
	v_exp_f32_e32 v12, v12
	v_exp_f32_e32 v13, v13
	s_nop 0
	v_pk_add_f32 v[12:13], v[12:13], v[8:9]
	v_pk_mul_f32 v[12:13], v[12:13], v[28:29]
	v_cvt_pk_bf16_f32 v12, v12, v13
	global_store_short v72, v12, s[90:91]
	s_add_u32 s90, s90, 0x4000
	s_addc_u32 s91, s91, 0
	global_store_short_d16_hi v72, v12, s[90:91]
	s_nop 7
	v_add_u32_e32 v70, s55, v3
	v_cvt_f32_i32_e32 v71, v70
	v_mul_f32_e32 v71, 0xb9b8b5c6, v71
	v_sub_u32_e32 v72, 0x1000, v70
	v_add_u32_e32 v73, 0x1000, v70
	v_cndmask_b32_e64 v72, v72, v73, s[14:15]
	v_lshlrev_b32_e32 v72, 1, v72
	s_mov_b64 s[90:91], s[84:85]
	s_nop 7
	v_mul_f32_e32 v10, s6, v71
	v_mul_f32_e32 v11, s7, v71
	v_exp_f32_e32 v10, v10
	v_exp_f32_e32 v11, v11
	s_nop 0
	v_pk_add_f32 v[10:11], v[10:11], v[8:9]
	v_pk_mul_f32 v[10:11], v[10:11], v[32:33]
	v_cvt_pk_bf16_f32 v10, v10, v11
	global_store_short v72, v10, s[90:91]
	s_add_u32 s90, s90, 0x4000
	s_addc_u32 s91, s91, 0
	global_store_short_d16_hi v72, v10, s[90:91]
	s_add_u32 s90, s90, 0x4000
	s_addc_u32 s91, s91, 0
	v_mul_f32_e32 v12, s10, v71
	v_mul_f32_e32 v13, s11, v71
	v_exp_f32_e32 v12, v12
	v_exp_f32_e32 v13, v13
	s_nop 0
	v_pk_add_f32 v[12:13], v[12:13], v[8:9]
	v_pk_mul_f32 v[12:13], v[12:13], v[34:35]
	v_cvt_pk_bf16_f32 v12, v12, v13
	global_store_short v72, v12, s[90:91]
	s_add_u32 s90, s90, 0x4000
	s_addc_u32 s91, s91, 0
	global_store_short_d16_hi v72, v12, s[90:91]
	s_add_u32 s90, s90, 0x4000
	s_addc_u32 s91, s91, 0
	v_mul_f32_e32 v10, s24, v71
	v_mul_f32_e32 v11, s26, v71
	v_exp_f32_e32 v10, v10
	v_exp_f32_e32 v11, v11
	s_nop 0
	v_pk_add_f32 v[10:11], v[10:11], v[8:9]
	v_pk_mul_f32 v[10:11], v[10:11], v[36:37]
	v_cvt_pk_bf16_f32 v10, v10, v11
	global_store_short v72, v10, s[90:91]
	s_add_u32 s90, s90, 0x4000
	s_addc_u32 s91, s91, 0
	global_store_short_d16_hi v72, v10, s[90:91]
	s_add_u32 s90, s90, 0x4000
	s_addc_u32 s91, s91, 0
	v_mul_f32_e32 v12, s32, v71
	v_mul_f32_e32 v13, s35, v71
	v_exp_f32_e32 v12, v12
	v_exp_f32_e32 v13, v13
	s_nop 0
	v_pk_add_f32 v[12:13], v[12:13], v[8:9]
	v_pk_mul_f32 v[12:13], v[12:13], v[38:39]
	v_cvt_pk_bf16_f32 v12, v12, v13
	global_store_short v72, v12, s[90:91]
	s_add_u32 s90, s90, 0x4000
	s_addc_u32 s91, s91, 0
	global_store_short_d16_hi v72, v12, s[90:91]
	s_add_u32 s90, s90, 0x4000
	s_addc_u32 s91, s91, 0
	v_mul_f32_e32 v10, s41, v71
	v_mul_f32_e32 v11, s44, v71
	v_exp_f32_e32 v10, v10
	v_exp_f32_e32 v11, v11
	s_nop 0
	v_pk_add_f32 v[10:11], v[10:11], v[8:9]
	v_pk_mul_f32 v[10:11], v[10:11], v[40:41]
	v_cvt_pk_bf16_f32 v10, v10, v11
	global_store_short v72, v10, s[90:91]
	s_add_u32 s90, s90, 0x4000
	s_addc_u32 s91, s91, 0
	global_store_short_d16_hi v72, v10, s[90:91]
	s_add_u32 s90, s90, 0x4000
	s_addc_u32 s91, s91, 0
	v_mul_f32_e32 v12, s45, v71
	v_mul_f32_e32 v13, s47, v71
	v_exp_f32_e32 v12, v12
	v_exp_f32_e32 v13, v13
	s_nop 0
	v_pk_add_f32 v[12:13], v[12:13], v[8:9]
	v_pk_mul_f32 v[12:13], v[12:13], v[42:43]
	v_cvt_pk_bf16_f32 v12, v12, v13
	global_store_short v72, v12, s[90:91]
	s_add_u32 s90, s90, 0x4000
	s_addc_u32 s91, s91, 0
	global_store_short_d16_hi v72, v12, s[90:91]
	s_add_u32 s90, s90, 0x4000
	s_addc_u32 s91, s91, 0
	v_mul_f32_e32 v10, s48, v71
	v_mul_f32_e32 v11, s49, v71
	v_exp_f32_e32 v10, v10
	v_exp_f32_e32 v11, v11
	s_nop 0
	v_pk_add_f32 v[10:11], v[10:11], v[8:9]
	v_pk_mul_f32 v[10:11], v[10:11], v[44:45]
	v_cvt_pk_bf16_f32 v10, v10, v11
	global_store_short v72, v10, s[90:91]
	s_add_u32 s90, s90, 0x4000
	s_addc_u32 s91, s91, 0
	global_store_short_d16_hi v72, v10, s[90:91]
	s_add_u32 s90, s90, 0x4000
	s_addc_u32 s91, s91, 0
	v_mul_f32_e32 v12, s52, v71
	v_mul_f32_e32 v13, s53, v71
	v_exp_f32_e32 v12, v12
	v_exp_f32_e32 v13, v13
	s_nop 0
	v_pk_add_f32 v[12:13], v[12:13], v[8:9]
	v_pk_mul_f32 v[12:13], v[12:13], v[46:47]
	v_cvt_pk_bf16_f32 v12, v12, v13
	global_store_short v72, v12, s[90:91]
	s_add_u32 s90, s90, 0x4000
	s_addc_u32 s91, s91, 0
	global_store_short_d16_hi v72, v12, s[90:91]
	s_barrier
	s_add_i32 s93, s93, s70
	s_branch .Lpf_item
